# K-loop phase rebalancing in all GEMM loops plus E-phase counted waits, without the next-tile prefetch (smaller modification surface)
# speedup vs baseline: 1.0055x; 1.0055x over previous
; #define STAGE(P, BASE, LD, br, kt) do { const bf16* _gb = BASE + ((long)(br) * (LD) + (long)(kt) * BK); \
;     _Pragma("unroll") for (int _i = 0; _i < 2; ++_i) { \
;       __builtin_amdgcn_global_load_lds((const unsigned*)(_gb + ((&LD == &lda) ? offA[_i] : offB[_i])), \
;         (unsigned*)((char*)(P) + tidx_ * 16 + _i * 8192), 16, 0, 0); } } while (0)
; #define WAIT_V(n) asm volatile("s_waitcnt vmcnt(" #n ")" ::: "memory")
; #define BAR __builtin_amdgcn_s_barrier()
; template <class Epi, int NB>
; DEV void gemm_tile_nb(const bf16* __restrict__ A, int lda, long strideA, const bf16* __restrict__ Bt, int ldb, long strideB, int K, int brow, int bcol, Epi& epi) {
;     ...
;   f32x4 acc[2][2][4][2] = {};
;   bf16x8 At[4][2], B0[2][2], B1[2][2];
;   const int nt = K / BK;
;   const int lane_off_ = (fr * 64 + fq * 16) ^ ((fr >> 3) << 5);
;   const int aoff = wr * 8192 + lane_off_, boff = 65536 + wc * 4096 + lane_off_;
;   unsigned offA[2], offB[2];
; #pragma unroll
;   for (int _i = 0; _i < 2; ++_i) { int _r, _c; stage_rc(tidx_ * 16 + _i * 8192, _r, _c); offA[_i] = (unsigned)(_r * lda + _c); offB[_i] = (unsigned)(_r * ldb + _c); }
; #pragma unroll 1
;   for (int br = 0; br < NB; ++br) {
;   STAGE(SB(0, 0), Bt, ldb, bcol, 0); STAGE(SA(0, 0), A, lda, brow, 0);
;   STAGE(SB(0, 1), Bt, ldb, bcol + HALF, 0); STAGE(SA(0, 1), A, lda, brow + HALF, 0);
;   if (wr == 1) BAR;
;   WAIT_V(4); BAR;
;   STAGE(SB(1, 0), Bt, ldb, bcol, 1); STAGE(SA(1, 0), A, lda, brow, 1); STAGE(SB(1, 1), Bt, ldb, bcol + HALF, 1);
;   WAIT_V(6); BAR;
.LBB0_767:
	v_and_b32_e32 v143, 15, v23
	s_bfe_u32 s1, s52, 0x20006
	v_bfe_u32 v142, v23, 4, 2
	v_lshlrev_b32_e32 v0, 6, v143
	v_lshlrev_b32_e32 v23, 2, v23
	v_lshl_or_b32 v0, v142, 4, v0
	v_and_b32_e32 v23, 32, v23
	s_lshl_b32 s41, s51, 13
	s_lshl_b32 s53, s1, 12
	v_add_u32_e32 v153, s13, v16
	v_bitop3_b32 v24, v0, s53, v23 bitop3:0xde
	v_bitop3_b32 v23, v0, s41, v23 bitop3:0xde
	s_mov_b64 s[54:55], 0x80
	v_readfirstlane_b32 s41, v153
	v_add_u32_e32 v154, 0x2000, v153
	v_lshl_add_u64 v[2:3], v[2:3], 0, s[54:55]
	s_mov_b32 m0, s41
	v_readfirstlane_b32 s41, v154
	v_add_u32_e32 v155, 0x8000, v146
	s_waitcnt vmcnt(4)
	s_barrier
	global_load_lds_dwordx4 v[2:3], off
	v_lshl_add_u64 v[2:3], v[6:7], 0, s[54:55]
	s_mov_b32 m0, s41
	v_readfirstlane_b32 s41, v155
	v_add_u32_e32 v156, 0xa000, v146
	global_load_lds_dwordx4 v[2:3], off
	v_lshl_add_u64 v[2:3], v[12:13], 0, s[54:55]
	s_mov_b32 m0, s41
	v_readfirstlane_b32 s41, v156
	v_add_u32_e32 v157, s14, v16
	global_load_lds_dwordx4 v[2:3], off
	v_lshl_add_u64 v[2:3], v[8:9], 0, s[54:55]
	s_mov_b32 m0, s41
	v_readfirstlane_b32 s41, v157
	v_add_u32_e32 v158, 0x2000, v157
	global_load_lds_dwordx4 v[2:3], off
	v_lshl_add_u64 v[2:3], v[10:11], 0, s[54:55]
	s_mov_b32 m0, s41
	v_readfirstlane_b32 s41, v158
	global_load_lds_dwordx4 v[2:3], off
	v_lshl_add_u64 v[2:3], v[4:5], 0, s[54:55]
	s_mov_b32 m0, s41
	v_lshlrev_b32_e32 v0, 13, v14
	global_load_lds_dwordx4 v[2:3], off
	v_and_b32_e32 v0, 0xffffc000, v0
	v_lshl_add_u32 v0, v15, 10, v0
	v_or_b32_e32 v0, v0, v17
	v_add_u32_sdwa v0, v0, sext(v18) dst_sel:DWORD dst_unused:UNUSED_PAD src0_sel:DWORD src1_sel:WORD_0
	v_lshlrev_b64 v[2:3], 1, v[0:1]
	v_lshlrev_b32_e32 v0, 13, v19
	v_and_b32_e32 v0, 0xffffc000, v0
	v_readlane_b32 s8, v254, 63
	v_lshl_add_u32 v0, v20, 10, v0
	s_add_u32 s44, s8, s44
	v_or_b32_e32 v0, v0, v21
	s_waitcnt vmcnt(6)
	s_addc_u32 s45, 0, s45
	v_add_u32_sdwa v0, v0, sext(v22) dst_sel:DWORD dst_unused:UNUSED_PAD src0_sel:DWORD src1_sel:WORD_0
	v_or_b32_e32 v24, 0x10000, v24
	v_lshl_add_u64 v[134:135], s[44:45], 0, v[2:3]
	v_lshlrev_b64 v[4:5], 1, v[0:1]
	v_lshl_add_u64 v[138:139], s[42:43], 0, v[2:3]
	v_mov_b32_e32 v2, 0
	v_lshl_add_u64 v[136:137], s[44:45], 0, v[4:5]
	v_lshl_add_u64 v[140:141], s[42:43], 0, v[4:5]
	s_mov_b32 s41, -2
	v_add_u32_e32 v144, 0, v24
	v_add_u32_e32 v0, 0, v23
	v_mov_b32_e32 v3, v2
	v_mov_b32_e32 v4, v2
	v_mov_b32_e32 v5, v2
	v_mov_b32_e32 v6, v2
	v_mov_b32_e32 v7, v2
	v_mov_b32_e32 v8, v2
	v_mov_b32_e32 v9, v2
	v_mov_b32_e32 v10, v2
	v_mov_b32_e32 v11, v2
	v_mov_b32_e32 v12, v2
	v_mov_b32_e32 v13, v2
	v_mov_b32_e32 v14, v2
	v_mov_b32_e32 v15, v2
	v_mov_b32_e32 v16, v2
	v_mov_b32_e32 v17, v2
	v_mov_b32_e32 v18, v2
	v_mov_b32_e32 v19, v2
	v_mov_b32_e32 v20, v2
	v_mov_b32_e32 v21, v2
	v_mov_b32_e32 v22, v2
	v_mov_b32_e32 v23, v2
	v_mov_b32_e32 v24, v2
	v_mov_b32_e32 v25, v2
	v_mov_b32_e32 v26, v2
	v_mov_b32_e32 v27, v2
	s_waitcnt vmcnt(0)
	v_mov_b32_e32 v28, v2
	v_mov_b32_e32 v29, v2
	v_mov_b32_e32 v30, v2
	v_mov_b32_e32 v31, v2
	v_mov_b32_e32 v32, v2
	v_mov_b32_e32 v33, v2
	v_mov_b32_e32 v34, v2
	v_mov_b32_e32 v35, v2
	v_mov_b32_e32 v36, v2
	v_mov_b32_e32 v37, v2
	v_mov_b32_e32 v38, v2
	v_mov_b32_e32 v39, v2
	v_mov_b32_e32 v40, v2
	v_mov_b32_e32 v41, v2
	v_mov_b32_e32 v42, v2
	v_mov_b32_e32 v43, v2
	v_mov_b32_e32 v44, v2
	v_mov_b32_e32 v45, v2
	v_mov_b32_e32 v46, v2
	v_mov_b32_e32 v47, v2
	v_mov_b32_e32 v48, v2
	v_mov_b32_e32 v49, v2
	v_mov_b32_e32 v50, v2
	v_mov_b32_e32 v51, v2
	v_mov_b32_e32 v52, v2
	v_mov_b32_e32 v53, v2
	v_mov_b32_e32 v54, v2
	v_mov_b32_e32 v55, v2
	v_mov_b32_e32 v56, v2
	v_mov_b32_e32 v57, v2
	v_mov_b32_e32 v58, v2
	v_mov_b32_e32 v59, v2
	v_mov_b32_e32 v60, v2
	v_mov_b32_e32 v61, v2
	v_mov_b32_e32 v62, v2
	v_mov_b32_e32 v63, v2
	v_mov_b32_e32 v64, v2
	v_mov_b32_e32 v65, v2
	v_mov_b32_e32 v70, v2
	v_mov_b32_e32 v71, v2
	v_mov_b32_e32 v72, v2
	v_mov_b32_e32 v73, v2
	v_mov_b32_e32 v86, v2
	v_mov_b32_e32 v87, v2
	v_mov_b32_e32 v88, v2
	v_mov_b32_e32 v89, v2
	v_mov_b32_e32 v90, v2
	v_mov_b32_e32 v91, v2
	v_mov_b32_e32 v92, v2
	v_mov_b32_e32 v93, v2
	v_mov_b32_e32 v94, v2
	v_mov_b32_e32 v95, v2
	v_mov_b32_e32 v96, v2
	v_mov_b32_e32 v97, v2
	v_mov_b32_e32 v98, v2
	v_mov_b32_e32 v99, v2
	v_mov_b32_e32 v100, v2
	v_mov_b32_e32 v101, v2
	v_mov_b32_e32 v102, v2
	v_mov_b32_e32 v103, v2
	v_mov_b32_e32 v104, v2
	v_mov_b32_e32 v105, v2
	v_mov_b32_e32 v106, v2
	v_mov_b32_e32 v107, v2
	v_mov_b32_e32 v108, v2
	v_mov_b32_e32 v109, v2
	v_mov_b32_e32 v110, v2
	v_mov_b32_e32 v111, v2
	v_mov_b32_e32 v112, v2
	v_mov_b32_e32 v113, v2
	v_mov_b32_e32 v114, v2
	v_mov_b32_e32 v115, v2
	v_mov_b32_e32 v116, v2
	v_mov_b32_e32 v117, v2
	v_mov_b32_e32 v118, v2
	v_mov_b32_e32 v119, v2
	v_mov_b32_e32 v120, v2
	v_mov_b32_e32 v121, v2
	v_mov_b32_e32 v122, v2
	v_mov_b32_e32 v123, v2
	v_mov_b32_e32 v124, v2
	v_mov_b32_e32 v125, v2
	v_mov_b32_e32 v126, v2
	v_mov_b32_e32 v127, v2
	v_mov_b32_e32 v128, v2
	v_mov_b32_e32 v129, v2
	v_mov_b32_e32 v66, v2
	v_mov_b32_e32 v67, v2
	v_mov_b32_e32 v68, v2
	v_mov_b32_e32 v69, v2
	v_mov_b32_e32 v74, v2
	v_mov_b32_e32 v75, v2
	v_mov_b32_e32 v76, v2
	v_mov_b32_e32 v77, v2
	v_mov_b32_e32 v78, v2
	v_mov_b32_e32 v79, v2
	v_mov_b32_e32 v80, v2
	v_mov_b32_e32 v81, v2
	v_mov_b32_e32 v82, v2
	v_mov_b32_e32 v83, v2
	v_mov_b32_e32 v84, v2
	v_mov_b32_e32 v85, v2
	s_mov_b64 s[44:45], 0xabe4080
	s_mov_b64 s[54:55], 0x2100100
	s_mov_b64 s[56:57], 0x2140100
	s_mov_b64 s[58:59], 0xabe4100
	s_mov_b64 s[60:61], 0x2100180
	s_mov_b64 s[62:63], 0x2140180
	s_barrier
	ds_read_b128 v[162:165], v144
	ds_read_b128 v[166:169], v144 offset:1024
	ds_read_b128 v[170:173], v144 offset:2048
	ds_read_b128 v[174:177], v144 offset:3072

; #define STAGE(P, BASE, LD, br, kt) do { const bf16* _gb = BASE + ((long)(br) * (LD) + (long)(kt) * BK); \
;     _Pragma("unroll") for (int _i = 0; _i < 2; ++_i) { \
;       __builtin_amdgcn_global_load_lds((const unsigned*)(_gb + ((&LD == &lda) ? offA[_i] : offB[_i])), \
;         (unsigned*)((char*)(P) + tidx_ * 16 + _i * 8192), 16, 0, 0); } } while (0)
; #define WAIT_V(n) asm volatile("s_waitcnt vmcnt(" #n ")" ::: "memory")
; #define BAR __builtin_amdgcn_s_barrier()
; template <class Epi, int NB>
; DEV void gemm_tile_nb(const bf16* __restrict__ A, int lda, long strideA, const bf16* __restrict__ Bt, int ldb, long strideB, int K, int brow, int bcol, Epi& epi) {
;     ...
;   f32x4 acc[2][2][4][2] = {};
;   bf16x8 At[4][2], B0[2][2], B1[2][2];
;   const int nt = K / BK;
;   const int lane_off_ = (fr * 64 + fq * 16) ^ ((fr >> 3) << 5);
;   const int aoff = wr * 8192 + lane_off_, boff = 65536 + wc * 4096 + lane_off_;
;   unsigned offA[2], offB[2];
; #pragma unroll
;   for (int _i = 0; _i < 2; ++_i) { int _r, _c; stage_rc(tidx_ * 16 + _i * 8192, _r, _c); offA[_i] = (unsigned)(_r * lda + _c); offB[_i] = (unsigned)(_r * ldb + _c); }
; #pragma unroll 1
;   for (int br = 0; br < NB; ++br) {
;   STAGE(SB(0, 0), Bt, ldb, bcol, 0); STAGE(SA(0, 0), A, lda, brow, 0);
;   STAGE(SB(0, 1), Bt, ldb, bcol + HALF, 0); STAGE(SA(0, 1), A, lda, brow + HALF, 0);
;   if (wr == 1) BAR;
;   WAIT_V(4); BAR;
;   STAGE(SB(1, 0), Bt, ldb, bcol, 1); STAGE(SA(1, 0), A, lda, brow, 1); STAGE(SB(1, 1), Bt, ldb, bcol + HALF, 1);
;   WAIT_V(6); BAR;
.LBB0_959:
	v_and_b32_e32 v143, 15, v23
	s_bfe_u32 s1, s57, 0x20006
	v_bfe_u32 v142, v23, 4, 2
	v_lshlrev_b32_e32 v0, 6, v143
	v_lshlrev_b32_e32 v23, 2, v23
	v_lshl_or_b32 v0, v142, 4, v0
	v_and_b32_e32 v23, 32, v23
	s_lshl_b32 s60, s56, 13
	s_lshl_b32 s61, s1, 12
	v_add_u32_e32 v153, s13, v15
	v_bitop3_b32 v24, v0, s61, v23 bitop3:0xde
	v_bitop3_b32 v23, v0, s60, v23 bitop3:0xde
	s_mov_b64 s[62:63], 0x80
	v_readfirstlane_b32 s60, v153
	v_add_u32_e32 v154, 0x2000, v153
	v_lshl_add_u64 v[2:3], v[2:3], 0, s[62:63]
	s_mov_b32 m0, s60
	v_readfirstlane_b32 s60, v154
	v_add_u32_e32 v155, 0x8000, v146
	s_waitcnt vmcnt(4)
	s_barrier
	global_load_lds_dwordx4 v[2:3], off
	v_lshl_add_u64 v[2:3], v[6:7], 0, s[62:63]
	s_mov_b32 m0, s60
	v_readfirstlane_b32 s60, v155
	v_add_u32_e32 v156, 0xa000, v146
	global_load_lds_dwordx4 v[2:3], off
	v_lshl_add_u64 v[2:3], v[12:13], 0, s[62:63]
	s_mov_b32 m0, s60
	v_readfirstlane_b32 s60, v156
	v_add_u32_e32 v157, s14, v15
	global_load_lds_dwordx4 v[2:3], off
	v_lshl_add_u64 v[2:3], v[8:9], 0, s[62:63]
	s_mov_b32 m0, s60
	v_readfirstlane_b32 s60, v157
	v_add_u32_e32 v158, 0x2000, v157
	global_load_lds_dwordx4 v[2:3], off
	v_lshl_add_u64 v[2:3], v[10:11], 0, s[62:63]
	s_mov_b32 m0, s60
	v_readfirstlane_b32 s60, v158
	global_load_lds_dwordx4 v[2:3], off
	v_lshl_add_u64 v[2:3], v[4:5], 0, s[62:63]
	s_mov_b32 m0, s60
	v_lshlrev_b32_e32 v0, 13, v14
	global_load_lds_dwordx4 v[2:3], off
	v_and_b32_e32 v0, 0xffffc000, v0
	v_lshl_add_u32 v0, v16, 10, v0
	v_or_b32_e32 v0, v0, v17
	v_add_u32_sdwa v0, v0, sext(v19) dst_sel:DWORD dst_unused:UNUSED_PAD src0_sel:DWORD src1_sel:WORD_0
	v_lshlrev_b64 v[2:3], 1, v[0:1]
	v_lshlrev_b32_e32 v0, 13, v18
	v_and_b32_e32 v0, 0xffffc000, v0
	v_lshl_add_u32 v0, v20, 10, v0
	v_or_b32_e32 v0, v0, v21
	s_add_u32 s42, s53, s42
	v_add_u32_sdwa v0, v0, sext(v22) dst_sel:DWORD dst_unused:UNUSED_PAD src0_sel:DWORD src1_sel:WORD_0
	s_addc_u32 s43, s54, s43
	v_lshlrev_b64 v[4:5], 1, v[0:1]
	v_lshl_add_u64 v[134:135], s[42:43], 0, v[2:3]
	v_lshl_add_u64 v[136:137], s[42:43], 0, v[4:5]
	s_lshl_b32 s42, s58, 11
	s_lshl_b32 s43, s59, 8
	s_add_i32 s42, s42, s43
	s_ashr_i32 s43, s42, 31
	s_lshl_b64 s[42:43], s[42:43], 11
	s_add_u32 s42, s50, s42
	s_waitcnt vmcnt(6)
	s_addc_u32 s43, s49, s43
	v_or_b32_e32 v24, 0x10000, v24
	v_lshl_add_u64 v[138:139], s[42:43], 0, v[2:3]
	v_mov_b32_e32 v2, 0
	v_lshl_add_u64 v[140:141], s[42:43], 0, v[4:5]
	s_mov_b32 s58, -2
	s_mov_b64 s[42:43], 0
	v_add_u32_e32 v145, 0, v24
	v_add_u32_e32 v0, 0, v23
	v_mov_b32_e32 v3, v2
	v_mov_b32_e32 v4, v2
	v_mov_b32_e32 v5, v2
	v_mov_b32_e32 v6, v2
	v_mov_b32_e32 v7, v2
	v_mov_b32_e32 v8, v2
	v_mov_b32_e32 v9, v2
	v_mov_b32_e32 v10, v2
	v_mov_b32_e32 v11, v2
	v_mov_b32_e32 v12, v2
	v_mov_b32_e32 v13, v2
	v_mov_b32_e32 v14, v2
	v_mov_b32_e32 v15, v2
	v_mov_b32_e32 v16, v2
	v_mov_b32_e32 v17, v2
	v_mov_b32_e32 v18, v2
	v_mov_b32_e32 v19, v2
	v_mov_b32_e32 v20, v2
	v_mov_b32_e32 v21, v2
	v_mov_b32_e32 v22, v2
	v_mov_b32_e32 v23, v2
	v_mov_b32_e32 v24, v2
	v_mov_b32_e32 v25, v2
	v_mov_b32_e32 v26, v2
	v_mov_b32_e32 v27, v2
	v_mov_b32_e32 v28, v2
	v_mov_b32_e32 v29, v2
	v_mov_b32_e32 v30, v2
	v_mov_b32_e32 v31, v2
	v_mov_b32_e32 v32, v2
	v_mov_b32_e32 v33, v2
	v_mov_b32_e32 v34, v2
	v_mov_b32_e32 v35, v2
	v_mov_b32_e32 v36, v2
	v_mov_b32_e32 v37, v2
	v_mov_b32_e32 v38, v2
	v_mov_b32_e32 v39, v2
	v_mov_b32_e32 v40, v2
	v_mov_b32_e32 v41, v2
	v_mov_b32_e32 v42, v2
	v_mov_b32_e32 v43, v2
	v_mov_b32_e32 v44, v2
	v_mov_b32_e32 v45, v2
	v_mov_b32_e32 v46, v2
	v_mov_b32_e32 v47, v2
	v_mov_b32_e32 v48, v2
	v_mov_b32_e32 v49, v2
	v_mov_b32_e32 v50, v2
	v_mov_b32_e32 v51, v2
	v_mov_b32_e32 v52, v2
	v_mov_b32_e32 v53, v2
	v_mov_b32_e32 v54, v2
	v_mov_b32_e32 v55, v2
	v_mov_b32_e32 v56, v2
	v_mov_b32_e32 v57, v2
	v_mov_b32_e32 v58, v2
	v_mov_b32_e32 v59, v2
	v_mov_b32_e32 v60, v2
	v_mov_b32_e32 v61, v2
	v_mov_b32_e32 v62, v2
	v_mov_b32_e32 v63, v2
	v_mov_b32_e32 v64, v2
	v_mov_b32_e32 v65, v2
	v_mov_b32_e32 v70, v2
	v_mov_b32_e32 v71, v2
	v_mov_b32_e32 v72, v2
	v_mov_b32_e32 v73, v2
	v_mov_b32_e32 v86, v2
	v_mov_b32_e32 v87, v2
	v_mov_b32_e32 v88, v2
	v_mov_b32_e32 v89, v2
	v_mov_b32_e32 v90, v2
	v_mov_b32_e32 v91, v2
	v_mov_b32_e32 v92, v2
	v_mov_b32_e32 v93, v2
	v_mov_b32_e32 v94, v2
	v_mov_b32_e32 v95, v2
	v_mov_b32_e32 v96, v2
	v_mov_b32_e32 v97, v2
	v_mov_b32_e32 v98, v2
	v_mov_b32_e32 v99, v2
	v_mov_b32_e32 v100, v2
	v_mov_b32_e32 v101, v2
	v_mov_b32_e32 v102, v2
	v_mov_b32_e32 v103, v2
	v_mov_b32_e32 v104, v2
	v_mov_b32_e32 v105, v2
	v_mov_b32_e32 v106, v2
	v_mov_b32_e32 v107, v2
	v_mov_b32_e32 v108, v2
	v_mov_b32_e32 v109, v2
	v_mov_b32_e32 v110, v2
	v_mov_b32_e32 v111, v2
	v_mov_b32_e32 v112, v2
	v_mov_b32_e32 v113, v2
	v_mov_b32_e32 v114, v2
	v_mov_b32_e32 v115, v2
	v_mov_b32_e32 v116, v2
	v_mov_b32_e32 v117, v2
	v_mov_b32_e32 v118, v2
	v_mov_b32_e32 v119, v2
	v_mov_b32_e32 v120, v2
	v_mov_b32_e32 v121, v2
	v_mov_b32_e32 v122, v2
	v_mov_b32_e32 v123, v2
	v_mov_b32_e32 v124, v2
	v_mov_b32_e32 v125, v2
	v_mov_b32_e32 v126, v2
	v_mov_b32_e32 v127, v2
	v_mov_b32_e32 v128, v2
	v_mov_b32_e32 v129, v2
	v_mov_b32_e32 v66, v2
	v_mov_b32_e32 v67, v2
	v_mov_b32_e32 v68, v2
	v_mov_b32_e32 v69, v2
	v_mov_b32_e32 v74, v2
	v_mov_b32_e32 v75, v2
	v_mov_b32_e32 v76, v2
	v_mov_b32_e32 v77, v2
	v_mov_b32_e32 v78, v2
	v_mov_b32_e32 v79, v2
	v_mov_b32_e32 v80, v2
	v_mov_b32_e32 v81, v2
	v_mov_b32_e32 v82, v2
	v_mov_b32_e32 v83, v2
	v_mov_b32_e32 v84, v2
	v_mov_b32_e32 v85, v2
	s_barrier
	ds_read_b128 v[162:165], v145
	ds_read_b128 v[166:169], v145 offset:1024
	ds_read_b128 v[170:173], v145 offset:2048
	ds_read_b128 v[174:177], v145 offset:3072
